# c4_diff_fastpath
# speedup vs baseline: 1.0131x; 1.0106x over previous
.Lresc_odd:
	v_cmp_gt_f32_e32 vcc, 1.0, v225
	s_cbranch_vccz .LBB0_1437
	s_and_saveexec_b64 s[54:55], s[4:5]
	ds_write_b32 v213, v225 offset:128
	s_or_b64 exec, exec, s[54:55]
	s_waitcnt lgkmcnt(0)
	ds_read_b128 v[4:7], v212 offset:224
	ds_read_b128 v[8:11], v212 offset:192
	ds_read_b128 v[12:15], v212 offset:160
	ds_read_b128 v[112:115], v212 offset:128
	s_waitcnt lgkmcnt(0)
	v_pk_mul_f32 v[78:79], v[78:79], v[6:7]
	v_pk_mul_f32 v[74:75], v[74:75], v[10:11]
	v_pk_mul_f32 v[70:71], v[70:71], v[14:15]
	v_pk_mul_f32 v[66:67], v[66:67], v[114:115]
	v_pk_mul_f32 v[76:77], v[76:77], v[4:5]
	v_pk_mul_f32 v[72:73], v[72:73], v[8:9]
	v_pk_mul_f32 v[68:69], v[68:69], v[12:13]
	v_pk_mul_f32 v[64:65], v[64:65], v[112:113]
	v_pk_mul_f32 v[62:63], v[6:7], v[62:63]
	v_pk_mul_f32 v[58:59], v[10:11], v[58:59]
	v_pk_mul_f32 v[54:55], v[14:15], v[54:55]
	v_pk_mul_f32 v[50:51], v[114:115], v[50:51]
	v_pk_mul_f32 v[60:61], v[4:5], v[60:61]
	v_pk_mul_f32 v[56:57], v[8:9], v[56:57]
	v_pk_mul_f32 v[52:53], v[12:13], v[52:53]
	v_pk_mul_f32 v[48:49], v[112:113], v[48:49]
	v_pk_mul_f32 v[46:47], v[6:7], v[46:47]
	v_pk_mul_f32 v[42:43], v[10:11], v[42:43]
	v_pk_mul_f32 v[38:39], v[14:15], v[38:39]
	v_pk_mul_f32 v[34:35], v[114:115], v[34:35]
	v_pk_mul_f32 v[44:45], v[4:5], v[44:45]
	v_pk_mul_f32 v[40:41], v[8:9], v[40:41]
	v_pk_mul_f32 v[36:37], v[12:13], v[36:37]
	v_pk_mul_f32 v[32:33], v[112:113], v[32:33]
	v_pk_mul_f32 v[30:31], v[6:7], v[30:31]
	v_pk_mul_f32 v[26:27], v[10:11], v[26:27]
	v_pk_mul_f32 v[22:23], v[14:15], v[22:23]
	v_pk_mul_f32 v[18:19], v[114:115], v[18:19]
	v_pk_mul_f32 v[28:29], v[4:5], v[28:29]
	v_pk_mul_f32 v[24:25], v[8:9], v[24:25]
	v_pk_mul_f32 v[20:21], v[12:13], v[20:21]
	v_pk_mul_f32 v[16:17], v[112:113], v[16:17]

.Lresc_even:
	v_cmp_gt_f32_e32 vcc, 1.0, v196
	s_cbranch_vccz .LBB0_1452
	s_and_saveexec_b64 s[54:55], s[4:5]
	ds_write_b32 v213, v196 offset:128
	s_or_b64 exec, exec, s[54:55]
	s_waitcnt lgkmcnt(0)
	ds_read_b128 v[4:7], v212 offset:224
	ds_read_b128 v[8:11], v212 offset:192
	ds_read_b128 v[12:15], v212 offset:160
	ds_read_b128 v[112:115], v212 offset:128
	s_waitcnt lgkmcnt(0)
	v_pk_mul_f32 v[78:79], v[78:79], v[6:7]
	v_pk_mul_f32 v[74:75], v[74:75], v[10:11]
	v_pk_mul_f32 v[70:71], v[70:71], v[14:15]
	v_pk_mul_f32 v[66:67], v[66:67], v[114:115]
	v_pk_mul_f32 v[76:77], v[76:77], v[4:5]
	v_pk_mul_f32 v[72:73], v[72:73], v[8:9]
	v_pk_mul_f32 v[68:69], v[68:69], v[12:13]
	v_pk_mul_f32 v[64:65], v[64:65], v[112:113]
	v_pk_mul_f32 v[62:63], v[6:7], v[62:63]
	v_pk_mul_f32 v[58:59], v[10:11], v[58:59]
	v_pk_mul_f32 v[54:55], v[14:15], v[54:55]
	v_pk_mul_f32 v[50:51], v[114:115], v[50:51]
	v_pk_mul_f32 v[60:61], v[4:5], v[60:61]
	v_pk_mul_f32 v[56:57], v[8:9], v[56:57]
	v_pk_mul_f32 v[52:53], v[12:13], v[52:53]
	v_pk_mul_f32 v[48:49], v[112:113], v[48:49]
	v_pk_mul_f32 v[46:47], v[6:7], v[46:47]
	v_pk_mul_f32 v[42:43], v[10:11], v[42:43]
	v_pk_mul_f32 v[38:39], v[14:15], v[38:39]
	v_pk_mul_f32 v[34:35], v[114:115], v[34:35]
	v_pk_mul_f32 v[44:45], v[4:5], v[44:45]
	v_pk_mul_f32 v[40:41], v[8:9], v[40:41]
	v_pk_mul_f32 v[36:37], v[12:13], v[36:37]
	v_pk_mul_f32 v[32:33], v[112:113], v[32:33]
	v_pk_mul_f32 v[30:31], v[6:7], v[30:31]
	v_pk_mul_f32 v[26:27], v[10:11], v[26:27]
	v_pk_mul_f32 v[22:23], v[14:15], v[22:23]
	v_pk_mul_f32 v[18:19], v[114:115], v[18:19]
	v_pk_mul_f32 v[28:29], v[4:5], v[28:29]
	v_pk_mul_f32 v[24:25], v[8:9], v[24:25]
	v_pk_mul_f32 v[20:21], v[12:13], v[20:21]
	v_pk_mul_f32 v[16:17], v[112:113], v[16:17]

.Lf_odd:
	v_max3_f32 v245, v128, v129, v130
	v_max3_f32 v246, v112, v113, v114
	v_max3_f32 v245, v245, v131, v132
	v_max3_f32 v246, v246, v115, v116
	v_max3_f32 v245, v245, v133, v134
	v_max3_f32 v246, v246, v117, v118
	v_max3_f32 v245, v245, v135, v136
	v_max3_f32 v246, v246, v119, v120
	v_max3_f32 v245, v245, v137, v138
	v_max3_f32 v246, v246, v121, v122
	v_max3_f32 v245, v245, v139, v140
	v_max3_f32 v246, v246, v123, v124
	v_max3_f32 v245, v245, v141, v142
	v_max3_f32 v246, v246, v125, v126
	v_max_f32_e32 v245, v245, v143
	v_max_f32_e32 v246, v246, v127
	v_max_f32_e32 v245, v245, v246
	v_mov_b32_e32 v246, v245
	s_nop 1
	v_permlane32_swap_b32_e32 v245, v246
	v_max_f32_e32 v245, v245, v246
	v_cmp_ge_f32_e32 vcc, s68, v245
	s_cmp_eq_u64 vcc, exec
	v_mov_b32_e32 v225, 1.0
	s_cbranch_scc0 .Lf_odd_resc
.Lf_odd_exp:
	v_exp_f32_e32 v96, v128
	v_exp_f32_e32 v80, v112
	v_exp_f32_e32 v97, v129
	v_exp_f32_e32 v81, v113
	v_exp_f32_e32 v98, v130
	v_exp_f32_e32 v82, v114
	v_exp_f32_e32 v99, v131
	v_exp_f32_e32 v83, v115
	v_exp_f32_e32 v100, v132
	v_exp_f32_e32 v84, v116
	v_exp_f32_e32 v101, v133
	v_exp_f32_e32 v85, v117
	v_exp_f32_e32 v102, v134
	v_exp_f32_e32 v86, v118
	v_exp_f32_e32 v103, v135
	v_exp_f32_e32 v87, v119
	v_exp_f32_e32 v104, v136
	v_exp_f32_e32 v88, v120
	v_exp_f32_e32 v105, v137
	v_exp_f32_e32 v89, v121
	v_exp_f32_e32 v106, v138
	v_exp_f32_e32 v90, v122
	v_exp_f32_e32 v107, v139
	v_exp_f32_e32 v91, v123
	v_exp_f32_e32 v108, v140
	v_exp_f32_e32 v92, v124
	v_exp_f32_e32 v109, v141
	v_exp_f32_e32 v93, v125
	v_exp_f32_e32 v110, v142
	v_exp_f32_e32 v94, v126
	v_exp_f32_e32 v111, v143
	v_exp_f32_e32 v95, v127
	ds_read_b64_tr_b16 v[114:115], v1 offset:0x200
	ds_read_b64_tr_b16 v[116:117], v1 offset:0xa00
	ds_read_b64_tr_b16 v[118:119], v1 offset:0x1200
	ds_read_b64_tr_b16 v[120:121], v1 offset:0x1a00
	ds_read_b64_tr_b16 v[122:123], v1 offset:0x2200
	ds_read_b64_tr_b16 v[124:125], v1 offset:0x2a00
	ds_read_b64_tr_b16 v[130:131], v1 offset:0x3200
	ds_read_b64_tr_b16 v[132:133], v1 offset:0x3a00
	s_waitcnt lgkmcnt(8)
	v_mfma_f32_32x32x16_bf16 v[64:79], v[166:169], v[182:185], v[64:79]
	v_mfma_f32_32x32x16_bf16 v[64:79], v[12:15], v[178:181], v[64:79]
	v_mfma_f32_32x32x16_bf16 v[64:79], v[8:11], v[174:177], v[64:79]
	v_mfma_f32_32x32x16_bf16 v[64:79], v[4:7], v[170:173], v[64:79]
	ds_read_b64_tr_b16 v[126:127], v1 offset:0x400
	ds_read_b64_tr_b16 v[128:129], v1 offset:0xc00
	ds_read_b64_tr_b16 v[134:135], v1 offset:0x1400
	ds_read_b64_tr_b16 v[136:137], v1 offset:0x1c00
	ds_read_b64_tr_b16 v[138:139], v1 offset:0x2400
	ds_read_b64_tr_b16 v[140:141], v1 offset:0x2c00
	ds_read_b64_tr_b16 v[170:171], v1 offset:0x3400
	ds_read_b64_tr_b16 v[172:173], v1 offset:0x3c00
	s_waitcnt lgkmcnt(8)
	v_mfma_f32_32x32x16_bf16 v[48:63], v[166:169], v[114:117], v[48:63]
	v_mfma_f32_32x32x16_bf16 v[48:63], v[12:15], v[118:121], v[48:63]
	v_mfma_f32_32x32x16_bf16 v[48:63], v[8:11], v[122:125], v[48:63]
	v_mfma_f32_32x32x16_bf16 v[48:63], v[4:7], v[130:133], v[48:63]
	ds_read_b64_tr_b16 v[112:113], v1 offset:0x600
	ds_read_b64_tr_b16 v[114:115], v1 offset:0xe00
	ds_read_b64_tr_b16 v[116:117], v1 offset:0x1600
	ds_read_b64_tr_b16 v[118:119], v1 offset:0x1e00
	ds_read_b64_tr_b16 v[120:121], v1 offset:0x2600
	ds_read_b64_tr_b16 v[122:123], v1 offset:0x2e00
	ds_read_b64_tr_b16 v[130:131], v1 offset:0x3600
	ds_read_b64_tr_b16 v[132:133], v1 offset:0x3e00
	s_waitcnt lgkmcnt(8)
	v_mfma_f32_32x32x16_bf16 v[32:47], v[166:169], v[126:129], v[32:47]
	v_mfma_f32_32x32x16_bf16 v[32:47], v[12:15], v[134:137], v[32:47]
	v_mfma_f32_32x32x16_bf16 v[32:47], v[8:11], v[138:141], v[32:47]
	v_mfma_f32_32x32x16_bf16 v[32:47], v[4:7], v[170:173], v[32:47]
	s_waitcnt lgkmcnt(0)
	v_mfma_f32_32x32x16_bf16 v[16:31], v[166:169], v[112:115], v[16:31]
	v_mfma_f32_32x32x16_bf16 v[16:31], v[12:15], v[116:119], v[16:31]
	v_mfma_f32_32x32x16_bf16 v[16:31], v[8:11], v[120:123], v[16:31]
	v_mfma_f32_32x32x16_bf16 v[16:31], v[4:7], v[130:133], v[16:31]
	s_branch .Lresc_odd
.Lf_odd_resc:
	v_add_f32_e32 v246, 0x42200000, v245
	v_min_f32_e32 v246, 0x42f00000, v246
	v_max3_f32 v245, v246, v245, 0
	v_exp_f32_e64 v225, -v245
	v_add_f32_e32 v221, v221, v245
	v_sub_f32_e32 v128, v128, v245
	v_sub_f32_e32 v129, v129, v245
	v_sub_f32_e32 v130, v130, v245
	v_sub_f32_e32 v131, v131, v245
	v_sub_f32_e32 v132, v132, v245
	v_sub_f32_e32 v133, v133, v245
	v_sub_f32_e32 v134, v134, v245
	v_sub_f32_e32 v135, v135, v245
	v_sub_f32_e32 v136, v136, v245
	v_sub_f32_e32 v137, v137, v245
	v_sub_f32_e32 v138, v138, v245
	v_sub_f32_e32 v139, v139, v245
	v_sub_f32_e32 v140, v140, v245
	v_sub_f32_e32 v141, v141, v245
	v_sub_f32_e32 v142, v142, v245
	v_sub_f32_e32 v143, v143, v245
	v_sub_f32_e32 v112, v112, v245
	v_sub_f32_e32 v113, v113, v245
	v_sub_f32_e32 v114, v114, v245
	v_sub_f32_e32 v115, v115, v245
	v_sub_f32_e32 v116, v116, v245
	v_sub_f32_e32 v117, v117, v245
	v_sub_f32_e32 v118, v118, v245
	v_sub_f32_e32 v119, v119, v245
	v_sub_f32_e32 v120, v120, v245
	v_sub_f32_e32 v121, v121, v245
	v_sub_f32_e32 v122, v122, v245
	v_sub_f32_e32 v123, v123, v245
	v_sub_f32_e32 v124, v124, v245
	v_sub_f32_e32 v125, v125, v245
	v_sub_f32_e32 v126, v126, v245
	v_sub_f32_e32 v127, v127, v245
	s_branch .Lf_odd_exp
.Lf_even:
	v_max3_f32 v245, v128, v129, v130
	v_max3_f32 v246, v112, v113, v114
	v_max3_f32 v245, v245, v131, v132
	v_max3_f32 v246, v246, v115, v116
	v_max3_f32 v245, v245, v133, v134
	v_max3_f32 v246, v246, v117, v118
	v_max3_f32 v245, v245, v135, v136
	v_max3_f32 v246, v246, v119, v120
	v_max3_f32 v245, v245, v137, v138
	v_max3_f32 v246, v246, v121, v122
	v_max3_f32 v245, v245, v139, v140
	v_max3_f32 v246, v246, v123, v124
	v_max3_f32 v245, v245, v141, v142
	v_max3_f32 v246, v246, v125, v126
	v_max_f32_e32 v245, v245, v143
	v_max_f32_e32 v246, v246, v127
	v_max_f32_e32 v245, v245, v246
	v_mov_b32_e32 v246, v245
	s_nop 1
	v_permlane32_swap_b32_e32 v245, v246
	v_max_f32_e32 v245, v245, v246
	v_cmp_ge_f32_e32 vcc, s68, v245
	s_cmp_eq_u64 vcc, exec
	v_mov_b32_e32 v196, 1.0
	s_cbranch_scc0 .Lf_even_resc
.Lf_even_exp:
	v_exp_f32_e32 v96, v128
	v_exp_f32_e32 v80, v112
	v_exp_f32_e32 v97, v129
	v_exp_f32_e32 v81, v113
	v_exp_f32_e32 v98, v130
	v_exp_f32_e32 v82, v114
	v_exp_f32_e32 v99, v131
	v_exp_f32_e32 v83, v115
	v_exp_f32_e32 v100, v132
	v_exp_f32_e32 v84, v116
	v_exp_f32_e32 v101, v133
	v_exp_f32_e32 v85, v117
	v_exp_f32_e32 v102, v134
	v_exp_f32_e32 v86, v118
	v_exp_f32_e32 v103, v135
	v_exp_f32_e32 v87, v119
	v_exp_f32_e32 v104, v136
	v_exp_f32_e32 v88, v120
	v_exp_f32_e32 v105, v137
	v_exp_f32_e32 v89, v121
	v_exp_f32_e32 v106, v138
	v_exp_f32_e32 v90, v122
	v_exp_f32_e32 v107, v139
	v_exp_f32_e32 v91, v123
	v_exp_f32_e32 v108, v140
	v_exp_f32_e32 v92, v124
	v_exp_f32_e32 v109, v141
	v_exp_f32_e32 v93, v125
	v_exp_f32_e32 v110, v142
	v_exp_f32_e32 v94, v126
	v_exp_f32_e32 v111, v143
	v_exp_f32_e32 v95, v127
	ds_read_b64_tr_b16 v[114:115], v162 offset:0x200
	ds_read_b64_tr_b16 v[116:117], v162 offset:0xa00
	ds_read_b64_tr_b16 v[118:119], v162 offset:0x1200
	ds_read_b64_tr_b16 v[120:121], v162 offset:0x1a00
	ds_read_b64_tr_b16 v[122:123], v162 offset:0x2200
	ds_read_b64_tr_b16 v[124:125], v162 offset:0x2a00
	ds_read_b64_tr_b16 v[130:131], v162 offset:0x3200
	ds_read_b64_tr_b16 v[132:133], v162 offset:0x3a00
	s_waitcnt lgkmcnt(8)
	v_mfma_f32_32x32x16_bf16 v[64:79], v[166:169], v[182:185], v[64:79]
	v_mfma_f32_32x32x16_bf16 v[64:79], v[12:15], v[178:181], v[64:79]
	v_mfma_f32_32x32x16_bf16 v[64:79], v[8:11], v[174:177], v[64:79]
	v_mfma_f32_32x32x16_bf16 v[64:79], v[4:7], v[170:173], v[64:79]
	ds_read_b64_tr_b16 v[126:127], v162 offset:0x400
	ds_read_b64_tr_b16 v[128:129], v162 offset:0xc00
	ds_read_b64_tr_b16 v[134:135], v162 offset:0x1400
	ds_read_b64_tr_b16 v[136:137], v162 offset:0x1c00
	ds_read_b64_tr_b16 v[138:139], v162 offset:0x2400
	ds_read_b64_tr_b16 v[140:141], v162 offset:0x2c00
	ds_read_b64_tr_b16 v[170:171], v162 offset:0x3400
	ds_read_b64_tr_b16 v[172:173], v162 offset:0x3c00
	s_waitcnt lgkmcnt(8)
	v_mfma_f32_32x32x16_bf16 v[48:63], v[166:169], v[114:117], v[48:63]
	v_mfma_f32_32x32x16_bf16 v[48:63], v[12:15], v[118:121], v[48:63]
	v_mfma_f32_32x32x16_bf16 v[48:63], v[8:11], v[122:125], v[48:63]
	v_mfma_f32_32x32x16_bf16 v[48:63], v[4:7], v[130:133], v[48:63]
	ds_read_b64_tr_b16 v[112:113], v162 offset:0x600
	ds_read_b64_tr_b16 v[114:115], v162 offset:0xe00
	ds_read_b64_tr_b16 v[116:117], v162 offset:0x1600
	ds_read_b64_tr_b16 v[118:119], v162 offset:0x1e00
	ds_read_b64_tr_b16 v[120:121], v162 offset:0x2600
	ds_read_b64_tr_b16 v[122:123], v162 offset:0x2e00
	ds_read_b64_tr_b16 v[130:131], v162 offset:0x3600
	ds_read_b64_tr_b16 v[132:133], v162 offset:0x3e00
	s_waitcnt lgkmcnt(8)
	v_mfma_f32_32x32x16_bf16 v[32:47], v[166:169], v[126:129], v[32:47]
	v_mfma_f32_32x32x16_bf16 v[32:47], v[12:15], v[134:137], v[32:47]
	v_mfma_f32_32x32x16_bf16 v[32:47], v[8:11], v[138:141], v[32:47]
	v_mfma_f32_32x32x16_bf16 v[32:47], v[4:7], v[170:173], v[32:47]
	s_waitcnt lgkmcnt(0)
	v_mfma_f32_32x32x16_bf16 v[16:31], v[166:169], v[112:115], v[16:31]
	v_mfma_f32_32x32x16_bf16 v[16:31], v[12:15], v[116:119], v[16:31]
	v_mfma_f32_32x32x16_bf16 v[16:31], v[8:11], v[120:123], v[16:31]
	v_mfma_f32_32x32x16_bf16 v[16:31], v[4:7], v[130:133], v[16:31]
	s_branch .Lresc_even
.Lf_even_resc:
	v_add_f32_e32 v246, 0x42200000, v245
	v_min_f32_e32 v246, 0x42f00000, v246
	v_max3_f32 v245, v246, v245, 0
	v_exp_f32_e64 v196, -v245
	v_add_f32_e32 v221, v221, v245
	v_sub_f32_e32 v128, v128, v245
	v_sub_f32_e32 v129, v129, v245
	v_sub_f32_e32 v130, v130, v245
	v_sub_f32_e32 v131, v131, v245
	v_sub_f32_e32 v132, v132, v245
	v_sub_f32_e32 v133, v133, v245
	v_sub_f32_e32 v134, v134, v245
	v_sub_f32_e32 v135, v135, v245
	v_sub_f32_e32 v136, v136, v245
	v_sub_f32_e32 v137, v137, v245
	v_sub_f32_e32 v138, v138, v245
	v_sub_f32_e32 v139, v139, v245
	v_sub_f32_e32 v140, v140, v245
	v_sub_f32_e32 v141, v141, v245
	v_sub_f32_e32 v142, v142, v245
	v_sub_f32_e32 v143, v143, v245
	v_sub_f32_e32 v112, v112, v245
	v_sub_f32_e32 v113, v113, v245
	v_sub_f32_e32 v114, v114, v245
	v_sub_f32_e32 v115, v115, v245
	v_sub_f32_e32 v116, v116, v245
	v_sub_f32_e32 v117, v117, v245
	v_sub_f32_e32 v118, v118, v245
	v_sub_f32_e32 v119, v119, v245
	v_sub_f32_e32 v120, v120, v245
	v_sub_f32_e32 v121, v121, v245
	v_sub_f32_e32 v122, v122, v245
	v_sub_f32_e32 v123, v123, v245
	v_sub_f32_e32 v124, v124, v245
	v_sub_f32_e32 v125, v125, v245
	v_sub_f32_e32 v126, v126, v245
	v_sub_f32_e32 v127, v127, v245
	s_branch .Lf_even_exp
